# attnA main loop label aligned to a 64-byte fetch boundary (two s_nop in front of the loop), otherwise as the wide-store version
# baseline (speedup 1.0000x reference)
; #define A_WAITBAR(ahead) do { if ((ahead) >= 2) asm volatile("s_waitcnt vmcnt(8)" ::: "memory"); else if ((ahead) == 1) asm volatile("s_waitcnt vmcnt(4)" ::: "memory"); else asm volatile("s_waitcnt vmcnt(0)" ::: "memory"); \
;         __builtin_amdgcn_s_barrier(); asm volatile("" ::: "memory"); } while (0)
; __device__ __forceinline__ void attnA_unit(const P2Ctx& C, int b, int h, int qb) {
;     ...
;       { const int lastt = NT - 1 < 2 ? NT - 1 : 2; A_WAITBAR(lastt - 1); } }
;     for (int kt = 1; kt < NT; ++kt) {
.LaA_wd_6:
	s_barrier
	s_mov_b32 s14, 1
	s_nop 0
	s_nop 0

; #define LAS __attribute__((address_space(3)))
; __device__ __forceinline__ void attnA_unit(const P2Ctx& C, int b, int h, int qb) {
;     ...
;     l += __shfl_xor(l, 32);
;     const float inv = 1.0f / l;
;     LAS float* X2 = (LAS float*)(lds + 65536);
;     if (comp == 1) {
; #pragma unroll
;         for (int cb = 0; cb < 4; ++cb)
; #pragma unroll
;             for (int r = 0; r < 16; ++r) X2[((qs * 4 + cb) * 16 + r) * 64 + lane] = o[cb][r] * inv;
;     }
;     __syncthreads();
.LaA_nofinalpv_14:
	s_waitcnt lgkmcnt(0)
	s_barrier
	v_mov_b32_e32 v243, v241
	s_nop 1
	v_permlane32_swap_b32 v243, v241
	v_add_f32_e32 v241, v243, v241
	v_rcp_f32_e32 v241, v241
	s_lshl_b32 s6, s9, 14
	s_add_i32 s6, s6, 0x10000
	v_lshlrev_b32_e32 v2, 2, v219
	v_add_u32_e32 v2, s6, v2
	s_cmp_eq_u32 s8, 0
	s_cbranch_scc1 .LaA_comp0_15
	s_nop 7
	s_nop 3
	v_mul_f32_e32 v68, v4, v241
	ds_write_b32 v2, v68 offset:0
	v_mul_f32_e32 v69, v5, v241
	ds_write_b32 v2, v69 offset:256
	v_mul_f32_e32 v68, v6, v241
	ds_write_b32 v2, v68 offset:512
	v_mul_f32_e32 v69, v7, v241
	ds_write_b32 v2, v69 offset:768
	v_mul_f32_e32 v68, v8, v241
	ds_write_b32 v2, v68 offset:1024
	v_mul_f32_e32 v69, v9, v241
	ds_write_b32 v2, v69 offset:1280
	v_mul_f32_e32 v68, v10, v241
	ds_write_b32 v2, v68 offset:1536
	v_mul_f32_e32 v69, v11, v241
	ds_write_b32 v2, v69 offset:1792
	v_mul_f32_e32 v68, v12, v241
	ds_write_b32 v2, v68 offset:2048
	v_mul_f32_e32 v69, v13, v241
	ds_write_b32 v2, v69 offset:2304
	v_mul_f32_e32 v68, v14, v241
	ds_write_b32 v2, v68 offset:2560
	v_mul_f32_e32 v69, v15, v241
	ds_write_b32 v2, v69 offset:2816
	v_mul_f32_e32 v68, v16, v241
	ds_write_b32 v2, v68 offset:3072
	v_mul_f32_e32 v69, v17, v241
	ds_write_b32 v2, v69 offset:3328
	v_mul_f32_e32 v68, v18, v241
	ds_write_b32 v2, v68 offset:3584
	v_mul_f32_e32 v69, v19, v241
	ds_write_b32 v2, v69 offset:3840
	v_mul_f32_e32 v68, v20, v241
	ds_write_b32 v2, v68 offset:4096
	v_mul_f32_e32 v69, v21, v241
	ds_write_b32 v2, v69 offset:4352
	v_mul_f32_e32 v68, v22, v241
	ds_write_b32 v2, v68 offset:4608
	v_mul_f32_e32 v69, v23, v241
	ds_write_b32 v2, v69 offset:4864
	v_mul_f32_e32 v68, v24, v241
	ds_write_b32 v2, v68 offset:5120
	v_mul_f32_e32 v69, v25, v241
	ds_write_b32 v2, v69 offset:5376
	v_mul_f32_e32 v68, v26, v241
	ds_write_b32 v2, v68 offset:5632
	v_mul_f32_e32 v69, v27, v241
	ds_write_b32 v2, v69 offset:5888
	v_mul_f32_e32 v68, v28, v241
	ds_write_b32 v2, v68 offset:6144
	v_mul_f32_e32 v69, v29, v241
	ds_write_b32 v2, v69 offset:6400
	v_mul_f32_e32 v68, v30, v241
	ds_write_b32 v2, v68 offset:6656
	v_mul_f32_e32 v69, v31, v241
	ds_write_b32 v2, v69 offset:6912
	v_mul_f32_e32 v68, v32, v241
	ds_write_b32 v2, v68 offset:7168
	v_mul_f32_e32 v69, v33, v241
	ds_write_b32 v2, v69 offset:7424
	v_mul_f32_e32 v68, v34, v241
	ds_write_b32 v2, v68 offset:7680
	v_mul_f32_e32 v69, v35, v241
	ds_write_b32 v2, v69 offset:7936
	v_mul_f32_e32 v68, v36, v241
	ds_write_b32 v2, v68 offset:8192
	v_mul_f32_e32 v69, v37, v241
	ds_write_b32 v2, v69 offset:8448
	v_mul_f32_e32 v68, v38, v241
	ds_write_b32 v2, v68 offset:8704
	v_mul_f32_e32 v69, v39, v241
	ds_write_b32 v2, v69 offset:8960
	v_mul_f32_e32 v68, v40, v241
	ds_write_b32 v2, v68 offset:9216
	v_mul_f32_e32 v69, v41, v241
	ds_write_b32 v2, v69 offset:9472
	v_mul_f32_e32 v68, v42, v241
	ds_write_b32 v2, v68 offset:9728
	v_mul_f32_e32 v69, v43, v241
	ds_write_b32 v2, v69 offset:9984
	v_mul_f32_e32 v68, v44, v241
	ds_write_b32 v2, v68 offset:10240
	v_mul_f32_e32 v69, v45, v241
	ds_write_b32 v2, v69 offset:10496
	v_mul_f32_e32 v68, v46, v241
	ds_write_b32 v2, v68 offset:10752
	v_mul_f32_e32 v69, v47, v241
	ds_write_b32 v2, v69 offset:11008
	v_mul_f32_e32 v68, v48, v241
	ds_write_b32 v2, v68 offset:11264
	v_mul_f32_e32 v69, v49, v241
	ds_write_b32 v2, v69 offset:11520
	v_mul_f32_e32 v68, v50, v241
	ds_write_b32 v2, v68 offset:11776
	v_mul_f32_e32 v69, v51, v241
	ds_write_b32 v2, v69 offset:12032
	v_mul_f32_e32 v68, v52, v241
	ds_write_b32 v2, v68 offset:12288
	v_mul_f32_e32 v69, v53, v241
	ds_write_b32 v2, v69 offset:12544
	v_mul_f32_e32 v68, v54, v241
	ds_write_b32 v2, v68 offset:12800
	v_mul_f32_e32 v69, v55, v241
	ds_write_b32 v2, v69 offset:13056
	v_mul_f32_e32 v68, v56, v241
	ds_write_b32 v2, v68 offset:13312
	v_mul_f32_e32 v69, v57, v241
	ds_write_b32 v2, v69 offset:13568
	v_mul_f32_e32 v68, v58, v241
	ds_write_b32 v2, v68 offset:13824
	v_mul_f32_e32 v69, v59, v241
	ds_write_b32 v2, v69 offset:14080
	v_mul_f32_e32 v68, v60, v241
	ds_write_b32 v2, v68 offset:14336
	v_mul_f32_e32 v69, v61, v241
	ds_write_b32 v2, v69 offset:14592
	v_mul_f32_e32 v68, v62, v241
	ds_write_b32 v2, v68 offset:14848
	v_mul_f32_e32 v69, v63, v241
	ds_write_b32 v2, v69 offset:15104
	v_mul_f32_e32 v68, v64, v241
	ds_write_b32 v2, v68 offset:15360
	v_mul_f32_e32 v69, v65, v241
	ds_write_b32 v2, v69 offset:15616
	v_mul_f32_e32 v68, v66, v241
	ds_write_b32 v2, v68 offset:15872
	v_mul_f32_e32 v69, v67, v241
	ds_write_b32 v2, v69 offset:16128
	s_waitcnt lgkmcnt(0)
	s_barrier
	s_branch .LaA_epiend_16
; __device__ __forceinline__ void attnA_unit(const P2Ctx& C, int b, int h, int qb) {
;     ...
;     if (comp == 1) {
; #pragma unroll
;         for (int cb = 0; cb < 4; ++cb)
; #pragma unroll
;             for (int r = 0; r < 16; ++r) X2[((qs * 4 + cb) * 16 + r) * 64 + lane] = o[cb][r] * inv;
;     }
;     __syncthreads();
;     if (comp == 0) {
; #pragma unroll
;         for (int cb = 0; cb < 4; ++cb)
; #pragma unroll
;             for (int r = 0; r < 16; ++r) o[cb][r] = o[cb][r] * inv - lam * X2[((qs * 4 + cb) * 16 + r) * 64 + lane];
;         subln_store(o, C.a->in[I_SUBG], C.AO + qrow * DM + h * 128, lane);
;     }
;     __syncthreads();
	s_nop 0
	s_nop 0
	s_nop 0
	s_nop 0
	s_nop 0
	s_nop 0
	s_nop 0
	s_nop 0
	s_nop 0
	s_nop 0
	s_nop 0
	s_nop 0
	s_nop 0
	s_nop 0
	s_nop 0
	s_nop 0
	s_nop 0
	s_nop 0
	s_nop 0
	s_nop 0
	s_nop 0
	s_nop 0
	s_nop 0
	s_nop 0
	s_nop 0
	s_nop 0
	s_nop 0
	s_nop 0
	s_nop 0
	s_nop 0
	s_nop 0
	s_nop 0
	s_nop 0
	s_nop 0
	s_nop 0
	s_nop 0
	s_nop 0
	s_nop 0
	s_nop 0
	s_nop 0
	s_nop 0
	s_nop 0
	s_nop 0
	s_nop 0
	s_nop 0
	s_nop 0
	s_nop 0
	s_nop 0
	s_nop 0
	s_nop 0
	s_nop 0
	s_nop 0
	s_nop 0
	s_nop 0
	s_nop 0
	s_nop 0
	s_nop 0
	s_nop 0
	s_nop 0
	s_nop 0
	s_nop 0
	s_nop 0
	s_nop 0
	s_nop 0
	s_nop 0
	s_nop 0
	s_nop 0
	s_nop 0
	s_nop 0
	s_nop 0
	s_nop 0
	s_nop 0
	s_nop 0
	s_nop 0
	s_nop 0
	s_nop 0
	s_nop 0
	s_nop 0
	s_nop 0
	s_nop 0
	s_nop 0
	s_nop 0
	s_nop 0
	s_nop 0
	s_nop 0
	s_nop 0
	s_nop 0
	s_nop 0
	s_nop 0
	s_nop 0
	s_nop 0
	s_nop 0
	s_nop 0
	s_nop 0
	s_nop 0
	s_nop 0
	s_nop 0
	s_nop 0
	s_nop 0
	s_nop 0
	s_nop 0
	s_nop 0
	s_nop 0
	s_nop 0
	s_nop 0
	s_nop 0
	s_nop 0
	s_nop 0
	s_nop 0
	s_nop 0
	s_nop 0
	s_nop 0
	s_nop 0
	s_nop 0
	s_nop 0
	s_nop 0
	s_nop 0
	s_nop 0
	s_nop 0
	s_nop 0
	s_nop 0
	s_nop 0
	s_nop 0
	s_nop 0
	s_nop 0
	s_nop 0
	s_nop 0
	s_nop 0
	s_nop 0
	s_nop 0
	s_nop 0
	s_nop 0
	s_nop 0
	s_nop 0
	s_nop 0
	s_nop 0
	s_nop 0
	s_nop 0
	s_nop 0
	s_nop 0
	s_nop 0
	s_nop 0
	s_nop 0
	s_nop 0
	s_nop 0
	s_nop 0
	s_nop 0
	s_nop 0
	s_nop 0
	s_nop 0
	s_nop 0
	s_nop 0
	s_nop 0
	s_nop 0
	s_nop 0
	s_nop 0
	s_nop 0
	s_nop 0
	s_nop 0
	s_nop 0
	s_nop 0
	s_nop 0
	s_nop 0
	s_nop 0
	s_nop 0
	s_nop 0
	s_nop 0
	s_nop 0
	s_nop 0
	s_nop 0
	s_nop 0
	s_nop 0
	s_nop 0
	s_nop 0
	s_nop 0
	s_nop 0
	s_nop 0
	s_nop 0
	s_nop 0
	s_nop 0
	s_nop 0
	s_nop 0
	s_nop 0
	s_nop 0
	s_nop 0
	s_nop 0
	s_nop 0
	s_nop 0
	s_nop 0
	s_nop 0
	s_nop 0
	s_nop 0
	s_nop 0
	s_nop 0
	s_nop 0
	s_nop 0
	s_nop 0
	s_nop 0
	s_nop 0
	s_nop 0
	s_nop 0
	s_nop 0
	s_nop 0
	s_nop 0
	s_nop 0
	s_nop 0
	s_nop 0
	s_nop 0
	s_nop 0
	s_nop 0
	s_nop 0
	s_nop 0
	s_nop 0
	s_nop 0
	s_nop 0
	s_nop 0
	s_nop 0
	s_nop 0
	s_nop 0
	s_nop 0
	s_nop 0
	s_nop 0
	s_nop 0
	s_nop 0
	s_nop 0
	s_nop 0
	s_nop 0
	s_nop 0
	s_nop 0
	s_nop 0
	s_nop 0
	s_nop 0
	s_nop 0
	s_nop 0
	s_nop 0
	s_nop 0
	s_nop 0
	s_nop 0
	s_nop 0
	s_nop 0
	s_nop 0
	s_nop 0
	s_nop 0
	s_nop 0
	s_nop 0
	s_nop 0
	s_nop 0
	s_nop 0
	s_nop 0
	s_nop 0
	s_nop 0
	s_nop 0
	s_nop 0
	s_nop 0
	s_nop 0
	s_nop 0
	s_nop 0
	s_nop 0
	s_nop 0
	s_nop 0
	s_nop 0
	s_nop 0
	s_nop 0
	s_nop 0
	s_nop 0
	s_nop 0
	s_nop 0
	s_nop 0
	s_nop 0
	s_nop 0
	s_nop 0
	s_nop 0
	s_nop 0
	s_nop 0
	s_nop 0
	s_nop 0
	s_nop 0
	s_nop 0
	s_nop 0
	s_nop 0
	s_nop 0
	s_nop 0
	s_nop 0
	s_nop 0
	s_nop 0
	s_nop 0
	s_nop 0
	s_nop 0
	s_nop 0
	s_nop 0
	s_nop 0
	s_nop 0
	s_nop 0
	s_nop 0
	s_nop 0
	s_nop 0
	s_nop 0
	s_nop 0
	s_nop 0
	s_nop 0
	s_nop 0
	s_nop 0
	s_nop 0
	s_nop 0
	s_nop 0
	s_nop 0
	s_nop 0
	s_nop 0
	s_nop 0
	s_nop 0
	s_nop 0
	s_nop 0
	s_nop 0
	s_nop 0
	s_nop 0
	s_nop 0
	s_nop 0
	s_nop 0
	s_nop 0
	s_nop 0
	s_nop 0
	s_nop 0
	s_nop 0
	s_nop 0
	s_nop 0
	s_nop 0
	s_nop 0
	s_nop 0
	s_nop 0
	s_nop 0
	s_nop 0
	s_nop 0
	s_nop 0
	s_nop 0
	s_nop 0
	s_nop 0
	s_nop 0
	s_nop 0
	s_nop 0
	s_nop 0
	s_nop 0
	s_nop 0
	s_nop 0
	s_nop 0
	s_nop 0
	s_nop 0
	s_nop 0
	s_nop 0
	s_nop 0
	s_nop 0
	s_nop 0
	s_nop 0
	s_nop 0
	s_nop 0
	s_nop 0
	s_nop 0
	s_nop 0
	s_nop 0
	s_nop 0
	s_nop 0
	s_nop 0
	s_nop 0
	s_nop 0
	s_nop 0
	s_nop 0
	s_nop 0
	s_nop 0
	s_nop 0
	s_nop 0
	s_nop 0
	s_nop 0
	s_nop 0
	s_nop 0
	s_nop 0
	s_nop 0
	s_nop 0
	s_nop 0
	s_nop 0
	s_nop 0
	s_nop 0
	s_nop 0
	s_nop 0
	s_nop 0
	s_nop 0
	s_nop 0
	s_nop 0
	s_nop 0
	s_nop 0
	s_nop 0
	s_nop 0
	s_nop 0
	s_nop 0
	s_nop 0
	s_nop 0
	s_nop 0
	s_nop 0
	s_nop 0
	s_nop 0
	s_nop 0
	s_nop 0
	s_nop 0
	s_nop 0
	s_nop 0
	s_nop 0
	s_nop 0
	s_nop 0
	s_nop 0
	s_nop 0
	s_nop 0
	s_nop 0
	s_nop 0
	s_nop 0
	s_nop 0
	s_nop 0
	s_nop 0
	s_nop 0
	s_nop 0
	s_nop 0
	s_nop 0
	s_nop 0
	s_nop 0
	s_nop 0
	s_nop 0
	s_nop 0
	s_nop 0
	s_nop 0
	s_nop 0
	s_nop 0
	s_nop 0
	s_nop 0
	s_nop 0
	s_nop 0
	s_nop 0
	s_nop 0
	s_nop 0
	s_nop 0
	s_nop 0
	s_nop 0
	s_nop 0
	s_nop 0
	s_nop 0
	s_nop 0
	s_nop 0
	s_nop 0
	s_nop 0
	s_nop 0
	s_nop 0
	s_nop 0
	s_nop 0
	s_nop 0
	s_nop 0
	s_nop 0
	s_nop 0
	s_nop 0
	s_nop 0
	s_nop 0
	s_nop 0
	s_nop 0
	s_nop 0
	s_nop 0
	s_nop 0
	s_nop 0
	s_nop 0
	s_nop 0
	s_nop 0
	s_nop 0
	s_nop 0
	s_nop 0
	s_nop 0
	s_nop 0
	s_nop 0
	s_nop 0
	s_nop 0
	s_nop 0
	s_nop 0
	s_nop 0
	s_nop 0
	s_nop 0
	s_nop 0
	s_nop 0
	s_nop 0
	s_nop 0
	s_nop 0
	s_nop 0
	s_nop 0
	s_nop 0
	s_nop 0
	s_nop 0
	s_nop 0
	s_nop 0
	s_nop 0
	s_nop 0
	s_nop 0
	s_nop 0
	s_nop 0
	s_nop 0
	s_nop 0
	s_nop 0
	s_nop 0
	s_nop 0
	s_nop 0
	s_nop 0
	s_nop 0
	s_nop 0
	s_nop 0
	s_nop 0
	s_nop 0
	s_nop 0
	s_nop 0
	s_nop 0
	s_nop 0
	s_nop 0
	s_nop 0
	s_nop 0
	s_nop 0
	s_nop 0
	s_nop 0
	s_nop 0
	s_nop 0
	s_nop 0
	s_nop 0
	s_nop 0
	s_nop 0
	s_nop 0
	s_nop 0
	s_nop 0
	s_nop 0
	s_nop 0
	s_nop 0
	s_nop 0
	s_nop 0
	s_nop 0
	s_nop 0
	s_nop 0
	s_nop 0
	s_nop 0
	s_nop 0
	s_nop 0
	s_nop 0
	s_nop 0
	s_nop 0
	s_nop 0
	s_nop 0
	s_nop 0
	s_nop 0
	s_nop 0
	s_nop 0
	s_nop 0
	s_nop 0
	s_nop 0
	s_nop 0
	s_nop 0
	s_nop 0
	s_nop 0
	s_nop 0
	s_nop 0
	s_nop 0
	s_nop 0
	s_nop 0
	s_nop 0
	s_nop 0
	s_nop 0
	s_nop 0
	s_nop 0
	s_nop 0
	s_nop 0
	s_nop 0
	s_nop 0
	s_nop 0
	s_nop 0
	s_nop 0
	s_nop 0
	s_nop 0
	s_nop 0
	s_nop 0
	s_nop 0
	s_nop 0
	s_nop 0
	s_nop 0
	s_nop 0
	s_nop 0
	s_nop 0
	s_nop 0
	s_nop 0
	s_nop 0
	s_nop 0
	s_nop 0
	s_nop 0
	s_nop 0
	s_nop 0
	s_nop 0
	s_nop 0
	s_nop 0
	s_nop 0
	s_nop 0
	s_nop 0
	s_nop 0
	s_nop 0
	s_nop 0
	s_nop 0
	s_nop 0
	s_nop 0
	s_nop 0
	s_nop 0
	s_nop 0
	s_nop 0
	s_nop 0
	s_nop 0
	s_nop 0
	s_nop 0
	s_nop 0
	s_nop 0
	s_nop 0
	s_nop 0
	s_nop 0
	s_nop 0
	s_nop 0
	s_nop 0
	s_nop 0
	s_nop 0
	s_nop 0
	s_nop 0
	s_nop 0
	s_nop 0
	s_nop 0
	s_nop 0
	s_nop 0
	s_nop 0
	s_nop 0
	s_nop 0
	s_nop 0
	s_nop 0
	s_nop 0
	s_nop 0
	s_nop 0
	s_nop 0
	s_nop 0
	s_nop 0
	s_nop 0
	s_nop 0
	s_nop 0
	s_nop 0
	s_nop 0
	s_nop 0
	s_nop 0
	s_nop 0
	s_nop 0
	s_nop 0
	s_nop 0
	s_nop 0
	s_nop 0
	s_nop 0
	s_nop 0
	s_nop 0
	s_nop 0
	s_nop 0
	s_nop 0
	s_nop 0
	s_nop 0
	s_nop 0
	s_nop 0
	s_nop 0
	s_nop 0
	s_nop 0
	s_nop 0
	s_nop 0
	s_nop 0
	s_nop 0
	s_nop 0
	s_nop 0
	s_nop 0
	s_nop 0
	s_nop 0
	s_nop 0
	s_nop 0
	s_nop 0
	s_nop 0
	s_nop 0
	s_nop 0
	s_nop 0
